# code placement: the four GEMM K-loop body heads aligned to 64 bytes (.p2align 6, s_nop padding)
# speedup vs baseline: 1.0027x; 1.0027x over previous
; template <class Epi, class Sched, bool ALIGN_EPI = false, bool SP2 = false>
; __device__ __forceinline__ void gemm_phase(PG8_LAS unsigned char* lds, const Gemm g, const Sched& S, const Epi& E) {
;     ...
;         const bool has_next = S.next(ui + 1, nxt);
;         const char* nA = has_next ? (const char*)g.A + (size_t)nxt.pm * tstepA : cA; const char* nB = has_next ? (const char*)g.Bt + (size_t)nxt.pn * tstepB : cB;
.LBB0_160:
	s_ashr_i32 s55, s54, 31
	s_lshl_b64 s[2:3], s[54:55], 15
	v_readlane_b32 s8, v255, 15
	s_add_u32 s12, s8, s2
	v_readlane_b32 s2, v255, 16
	s_addc_u32 s13, s2, s3
	s_ashr_i32 s49, s48, 31
	s_lshl_b64 s[2:3], s[48:49], 19
	v_readlane_b32 s8, v255, 29
	s_add_u32 s46, s8, s2
	v_readlane_b32 s2, v255, 40
	s_addc_u32 s47, s2, s3
	s_add_u32 s28, s24, 0x800000
	s_addc_u32 s29, s25, 0
	s_add_u32 s42, s24, 0xc00000
	s_addc_u32 s43, s25, 0
	s_add_i32 s55, 0, 0x10000
	s_and_b64 s[2:3], s[30:31], exec
	s_cselect_b32 s27, s13, s25
	s_cselect_b32 s44, s12, s24
	s_add_i32 vcc_hi, 0, 0x14000
	v_add_u32_e32 v142, s55, v97
	v_add_u32_e32 v143, vcc_hi, v97
	ds_read_b128 v[0:3], v142
	ds_read_b128 v[4:7], v142 offset:1024
	ds_read_b128 v[8:11], v142 offset:2048
	ds_read_b128 v[12:15], v142 offset:3072
	ds_read_b128 v[16:19], v143
	ds_read_b128 v[20:23], v143 offset:1024
	ds_read_b128 v[24:27], v143 offset:2048
	ds_read_b128 v[28:31], v143 offset:3072
	v_writelane_b32 v255, s30, 33
	s_and_b64 s[2:3], s[30:31], exec
	s_cselect_b32 s45, s47, s1
	v_writelane_b32 v255, s31, 34
	s_cselect_b32 s49, s46, s0
	s_add_u32 s2, s24, 0x404000
	s_addc_u32 s3, s25, 0
	s_add_i32 s50, s22, 0xc000
	s_mov_b32 m0, s50
	s_add_i32 s51, s22, 0xe000
	ds_read_b128 v[32:35], v161
	ds_read_b128 v[36:39], v161 offset:1024
	ds_read_b128 v[40:43], v161 offset:2048
	ds_read_b128 v[44:47], v161 offset:3072
	ds_read_b128 v[48:51], v161 offset:4096
	ds_read_b128 v[52:55], v161 offset:5120
	ds_read_b128 v[56:59], v161 offset:6144
	ds_read_b128 v[60:63], v161 offset:7168
	global_load_lds_dwordx4 v130, s[2:3]
	s_mov_b32 m0, s51
	s_nop 0
	global_load_lds_dwordx4 v134, s[2:3]
	s_waitcnt vmcnt(8)
	s_waitcnt lgkmcnt(0)
	s_barrier
	v_mfma_f32_16x16x32_bf16 v[64:67], v[0:3], v[32:35], 0
	v_mfma_f32_16x16x32_bf16 v[68:71], v[8:11], v[32:35], 0
	v_mfma_f32_16x16x32_bf16 v[72:75], v[0:3], v[40:43], 0
	v_mfma_f32_16x16x32_bf16 v[76:79], v[8:11], v[40:43], 0
	v_mfma_f32_16x16x32_bf16 v[80:83], v[0:3], v[48:51], 0
	v_mfma_f32_16x16x32_bf16 v[84:87], v[8:11], v[48:51], 0
	v_mfma_f32_16x16x32_bf16 v[88:91], v[0:3], v[56:59], 0
	v_mfma_f32_16x16x32_bf16 v[92:95], v[8:11], v[56:59], 0
	v_mfma_f32_16x16x32_bf16 v[64:67], v[4:7], v[36:39], v[64:67]
	v_mfma_f32_16x16x32_bf16 v[68:71], v[12:15], v[36:39], v[68:71]
	v_mfma_f32_16x16x32_bf16 v[72:75], v[4:7], v[44:47], v[72:75]
	v_mfma_f32_16x16x32_bf16 v[76:79], v[12:15], v[44:47], v[76:79]
	v_mfma_f32_16x16x32_bf16 v[80:83], v[4:7], v[52:55], v[80:83]
	v_mfma_f32_16x16x32_bf16 v[84:87], v[12:15], v[52:55], v[84:87]
	v_mfma_f32_16x16x32_bf16 v[88:91], v[4:7], v[60:63], v[88:91]
	v_mfma_f32_16x16x32_bf16 v[98:101], v[12:15], v[60:63], v[92:95]
	v_mfma_f32_16x16x32_bf16 v[92:95], v[16:19], v[32:35], 0
	v_mfma_f32_16x16x32_bf16 v[32:35], v[24:27], v[32:35], 0
	v_mfma_f32_16x16x32_bf16 v[106:109], v[20:23], v[36:39], v[92:95]
	v_mfma_f32_16x16x32_bf16 v[32:35], v[28:31], v[36:39], v[32:35]
	v_mfma_f32_16x16x32_bf16 v[36:39], v[16:19], v[40:43], 0
	v_mfma_f32_16x16x32_bf16 v[40:43], v[24:27], v[40:43], 0
	v_mfma_f32_16x16x32_bf16 v[36:39], v[20:23], v[44:47], v[36:39]
	v_mfma_f32_16x16x32_bf16 v[40:43], v[28:31], v[44:47], v[40:43]
	v_mfma_f32_16x16x32_bf16 v[44:47], v[16:19], v[48:51], 0
	v_mfma_f32_16x16x32_bf16 v[48:51], v[24:27], v[48:51], 0
	v_mfma_f32_16x16x32_bf16 v[44:47], v[20:23], v[52:55], v[44:47]
	v_mfma_f32_16x16x32_bf16 v[48:51], v[28:31], v[52:55], v[48:51]
	v_mfma_f32_16x16x32_bf16 v[52:55], v[16:19], v[56:59], 0
	v_mfma_f32_16x16x32_bf16 v[56:59], v[24:27], v[56:59], 0
	v_mfma_f32_16x16x32_bf16 v[52:55], v[20:23], v[60:63], v[52:55]
	v_mfma_f32_16x16x32_bf16 v[56:59], v[28:31], v[60:63], v[56:59]
	s_barrier
	v_lshl_add_u64 v[158:159], s[0:1], 0, v[132:133]
	s_mov_b64 s[2:3], 0x100
	s_add_i32 s55, s55, s10
	v_lshl_add_u64 v[144:145], v[158:159], 0, s[2:3]
	s_mov_b32 m0, s55
	v_lshl_add_u64 v[178:179], s[0:1], 0, v[136:137]
	s_add_i32 vcc_lo, s55, 0x2000
	ds_read_b128 v[60:63], v161 offset:16384
	ds_read_b128 v[92:95], v161 offset:17408
	ds_read_b128 v[102:105], v161 offset:18432
	ds_read_b128 v[110:113], v161 offset:19456
	ds_read_b128 v[114:117], v161 offset:20480
	ds_read_b128 v[118:121], v161 offset:21504
	ds_read_b128 v[122:125], v161 offset:22528
	ds_read_b128 v[126:129], v161 offset:23552
	global_load_lds_dwordx4 v[144:145], off
	v_lshl_add_u64 v[144:145], v[178:179], 0, s[2:3]
	s_add_u32 s2, s0, 0x40100
	s_mov_b32 m0, vcc_lo
	s_addc_u32 s3, s1, 0
	s_add_i32 vcc_hi, vcc_hi, s10
	global_load_lds_dwordx4 v[144:145], off
	s_mov_b32 m0, vcc_hi
	s_add_i32 s56, vcc_hi, 0x2000
	global_load_lds_dwordx4 v132, s[2:3]
	s_mov_b32 m0, s56
	s_nop 0
	global_load_lds_dwordx4 v136, s[2:3]
	s_mov_b32 m0, s22
	s_nop 0
	global_load_lds_dwordx4 v130, s[28:29]
	s_mov_b32 m0, s23
	s_nop 0
	global_load_lds_dwordx4 v134, s[28:29]
	s_waitcnt vmcnt(8)
	s_waitcnt lgkmcnt(0)
	s_barrier
	v_mfma_f32_16x16x32_bf16 v[144:147], v[0:3], v[60:63], 0
	v_mfma_f32_16x16x32_bf16 v[154:157], v[0:3], v[102:105], 0
	v_mfma_f32_16x16x32_bf16 v[166:169], v[0:3], v[114:117], 0
	v_mfma_f32_16x16x32_bf16 v[0:3], v[0:3], v[122:125], 0
	v_mfma_f32_16x16x32_bf16 v[146:149], v[4:7], v[92:95], v[144:147]
	v_mfma_f32_16x16x32_bf16 v[154:157], v[4:7], v[110:113], v[154:157]
	v_mfma_f32_16x16x32_bf16 v[166:169], v[4:7], v[118:121], v[166:169]
	v_mfma_f32_16x16x32_bf16 v[0:3], v[4:7], v[126:129], v[0:3]
	v_mfma_f32_16x16x32_bf16 v[4:7], v[8:11], v[122:125], 0
	v_mfma_f32_16x16x32_bf16 v[150:153], v[8:11], v[60:63], 0
	v_mfma_f32_16x16x32_bf16 v[162:165], v[8:11], v[102:105], 0
	v_mfma_f32_16x16x32_bf16 v[170:173], v[8:11], v[114:117], 0
	v_mfma_f32_16x16x32_bf16 v[4:7], v[12:15], v[126:129], v[4:7]
	v_mfma_f32_16x16x32_bf16 v[150:153], v[12:15], v[92:95], v[150:153]
	v_mfma_f32_16x16x32_bf16 v[162:165], v[12:15], v[110:113], v[162:165]
	v_mfma_f32_16x16x32_bf16 v[170:173], v[12:15], v[118:121], v[170:173]
	v_mfma_f32_16x16x32_bf16 v[12:15], v[24:27], v[60:63], 0
	v_mfma_f32_16x16x32_bf16 v[174:177], v[28:31], v[92:95], v[12:15]
	v_mfma_f32_16x16x32_bf16 v[12:15], v[16:19], v[102:105], 0
	v_mfma_f32_16x16x32_bf16 v[180:183], v[20:23], v[110:113], v[12:15]
	v_mfma_f32_16x16x32_bf16 v[12:15], v[24:27], v[102:105], 0
	v_mfma_f32_16x16x32_bf16 v[184:187], v[28:31], v[110:113], v[12:15]
	v_mfma_f32_16x16x32_bf16 v[12:15], v[16:19], v[114:117], 0
	v_mfma_f32_16x16x32_bf16 v[188:191], v[20:23], v[118:121], v[12:15]
	v_mfma_f32_16x16x32_bf16 v[12:15], v[24:27], v[114:117], 0
	v_mfma_f32_16x16x32_bf16 v[8:11], v[16:19], v[60:63], 0
	v_mfma_f32_16x16x32_bf16 v[192:195], v[28:31], v[118:121], v[12:15]
	v_mfma_f32_16x16x32_bf16 v[12:15], v[16:19], v[122:125], 0
	v_mfma_f32_16x16x32_bf16 v[8:11], v[20:23], v[92:95], v[8:11]
	v_mfma_f32_16x16x32_bf16 v[196:199], v[20:23], v[126:129], v[12:15]
	v_mfma_f32_16x16x32_bf16 v[12:15], v[24:27], v[122:125], 0
	v_mfma_f32_16x16x32_bf16 v[200:203], v[28:31], v[126:129], v[12:15]
	s_barrier
	s_add_i32 s30, 0, 0x18000
	s_add_i32 s57, 0, 0x1c000
	v_add_u32_e32 v144, s30, v97
	v_add_u32_e32 v145, s57, v97
	s_nop 0
	ds_read_b128 v[12:15], v144
	ds_read_b128 v[16:19], v144 offset:1024
	ds_read_b128 v[24:27], v144 offset:2048
	ds_read_b128 v[204:207], v144 offset:3072
	ds_read_b128 v[208:211], v145
	ds_read_b128 v[212:215], v145 offset:1024
	ds_read_b128 v[216:219], v145 offset:2048
	ds_read_b128 v[220:223], v145 offset:3072
	s_add_u32 s2, s24, 0x804000
	s_addc_u32 s3, s25, 0
	s_mov_b32 m0, s39
	ds_read_b128 v[20:23], v161 offset:32768
	ds_read_b128 v[28:31], v161 offset:33792
	ds_read_b128 v[60:63], v161 offset:34816
	ds_read_b128 v[224:227], v161 offset:35840
	ds_read_b128 v[228:231], v161 offset:36864
	ds_read_b128 v[234:237], v161 offset:37888
	ds_read_b128 v[238:241], v161 offset:38912
	ds_read_b128 v[242:245], v161 offset:39936
	global_load_lds_dwordx4 v130, s[2:3]
	s_mov_b32 m0, s52
	s_nop 0
	global_load_lds_dwordx4 v134, s[2:3]
	s_waitcnt vmcnt(8)
	s_waitcnt lgkmcnt(0)
	s_barrier
	v_mfma_f32_16x16x32_bf16 v[64:67], v[12:15], v[20:23], v[64:67]
	v_mfma_f32_16x16x32_bf16 v[126:129], v[16:19], v[28:31], v[64:67]
	v_mfma_f32_16x16x32_bf16 v[64:67], v[24:27], v[20:23], v[68:71]
	v_mfma_f32_16x16x32_bf16 v[118:121], v[204:207], v[28:31], v[64:67]
	v_mfma_f32_16x16x32_bf16 v[64:67], v[12:15], v[60:63], v[72:75]
	v_mfma_f32_16x16x32_bf16 v[110:113], v[16:19], v[224:227], v[64:67]
	v_mfma_f32_16x16x32_bf16 v[64:67], v[24:27], v[60:63], v[76:79]
	v_mfma_f32_16x16x32_bf16 v[102:105], v[204:207], v[224:227], v[64:67]
	v_mfma_f32_16x16x32_bf16 v[64:67], v[12:15], v[228:231], v[80:83]
	v_mfma_f32_16x16x32_bf16 v[92:95], v[16:19], v[234:237], v[64:67]
	v_mfma_f32_16x16x32_bf16 v[64:67], v[24:27], v[228:231], v[84:87]
	v_mfma_f32_16x16x32_bf16 v[84:87], v[204:207], v[234:237], v[64:67]
	v_mfma_f32_16x16x32_bf16 v[64:67], v[12:15], v[238:241], v[88:91]
	v_mfma_f32_16x16x32_bf16 v[76:79], v[16:19], v[242:245], v[64:67]
	v_mfma_f32_16x16x32_bf16 v[64:67], v[24:27], v[238:241], v[98:101]
	v_mfma_f32_16x16x32_bf16 v[68:71], v[204:207], v[242:245], v[64:67]
	v_mfma_f32_16x16x32_bf16 v[64:67], v[208:211], v[20:23], v[106:109]
	v_mfma_f32_16x16x32_bf16 v[20:23], v[216:219], v[20:23], v[32:35]
	v_mfma_f32_16x16x32_bf16 v[114:117], v[220:223], v[28:31], v[20:23]
	v_mfma_f32_16x16x32_bf16 v[20:23], v[208:211], v[60:63], v[36:39]
	v_mfma_f32_16x16x32_bf16 v[106:109], v[212:215], v[224:227], v[20:23]
	v_mfma_f32_16x16x32_bf16 v[20:23], v[216:219], v[60:63], v[40:43]
	v_mfma_f32_16x16x32_bf16 v[98:101], v[220:223], v[224:227], v[20:23]
	v_mfma_f32_16x16x32_bf16 v[20:23], v[208:211], v[228:231], v[44:47]
	v_mfma_f32_16x16x32_bf16 v[88:91], v[212:215], v[234:237], v[20:23]
	v_mfma_f32_16x16x32_bf16 v[20:23], v[216:219], v[228:231], v[48:51]
	v_mfma_f32_16x16x32_bf16 v[80:83], v[220:223], v[234:237], v[20:23]
	v_mfma_f32_16x16x32_bf16 v[20:23], v[208:211], v[238:241], v[52:55]
	v_mfma_f32_16x16x32_bf16 v[72:75], v[212:215], v[242:245], v[20:23]
	v_mfma_f32_16x16x32_bf16 v[20:23], v[216:219], v[238:241], v[56:59]
	v_mfma_f32_16x16x32_bf16 v[122:125], v[212:215], v[28:31], v[64:67]
	v_mfma_f32_16x16x32_bf16 v[64:67], v[220:223], v[242:245], v[20:23]
	s_barrier
; template <class Epi, class Sched, bool ALIGN_EPI = false, bool SP2 = false>
; __device__ __forceinline__ void gemm_phase(PG8_LAS unsigned char* lds, const Gemm g, const Sched& S, const Epi& E) {
;     ...
;         if constexpr (Epi::PEEL) {
;             const char* a1 = cA + kstepA; const char* a2 = cA + 2 * kstepA; const char* b2 = cB + 2 * kstepB; const char* a3 = a2 + kstepA; const char* b3 = b2 + kstepB;
;             PG8_ITER(8);
;         }
;         for (int t = (Epi::PEEL ? 2 : 0); t < nt; t += 2) {
;             const bool last = (t == nt - 2);
;             const char* a1 = cA + (size_t)(t + 1) * kstepA;
;             const char* a2 = last ? nA : cA + (size_t)(t + 2) * kstepA; const char* b2 = last ? nB : cB + (size_t)(t + 2) * kstepB;
;             const char* a3 = a2 + kstepA; const char* b3 = b2 + kstepB;
;             PG8_ITER(8);
	s_mov_b64 s[2:3], 0x180
	s_add_i32 s30, s30, s10
	s_nop 1
	v_lshl_add_u64 v[20:21], v[158:159], 0, s[2:3]
	s_mov_b32 m0, s30
	s_add_i32 s31, s30, 0x2000
	ds_read_b128 v[32:35], v161 offset:49152
	ds_read_b128 v[40:43], v161 offset:50176
	ds_read_b128 v[224:227], v161 offset:51200
	ds_read_b128 v[228:231], v161 offset:52224
	ds_read_b128 v[234:237], v161 offset:53248
	ds_read_b128 v[238:241], v161 offset:54272
	ds_read_b128 v[242:245], v161 offset:55296
	ds_read_b128 v[246:249], v161 offset:56320
	global_load_lds_dwordx4 v[20:21], off
	v_lshl_add_u64 v[20:21], v[178:179], 0, s[2:3]
	s_add_u32 s2, s0, 0x40180
	s_mov_b32 m0, s31
	s_addc_u32 s3, s1, 0
	s_add_i32 s57, s57, s10
	global_load_lds_dwordx4 v[20:21], off
	s_mov_b32 m0, s57
	s_add_i32 s96, s57, 0x2000
	global_load_lds_dwordx4 v132, s[2:3]
	s_mov_b32 m0, s96
	s_nop 0
	global_load_lds_dwordx4 v136, s[2:3]
	s_mov_b32 m0, s11
	s_nop 0
	global_load_lds_dwordx4 v130, s[42:43]
	s_mov_b32 m0, s19
	s_nop 0
	global_load_lds_dwordx4 v134, s[42:43]
	s_waitcnt vmcnt(8)
	s_waitcnt lgkmcnt(0)
	s_barrier
	v_mfma_f32_16x16x32_bf16 v[20:23], v[12:15], v[32:35], v[146:149]
	v_mfma_f32_16x16x32_bf16 v[60:63], v[16:19], v[40:43], v[20:23]
	v_mfma_f32_16x16x32_bf16 v[20:23], v[24:27], v[32:35], v[150:153]
	v_mfma_f32_16x16x32_bf16 v[52:55], v[204:207], v[40:43], v[20:23]
	v_mfma_f32_16x16x32_bf16 v[20:23], v[12:15], v[224:227], v[154:157]
	v_mfma_f32_16x16x32_bf16 v[44:47], v[16:19], v[228:231], v[20:23]
	v_mfma_f32_16x16x32_bf16 v[20:23], v[24:27], v[224:227], v[162:165]
	v_mfma_f32_16x16x32_bf16 v[36:39], v[204:207], v[228:231], v[20:23]
	v_mfma_f32_16x16x32_bf16 v[20:23], v[12:15], v[234:237], v[166:169]
	v_mfma_f32_16x16x32_bf16 v[0:3], v[12:15], v[242:245], v[0:3]
	v_mfma_f32_16x16x32_bf16 v[28:31], v[16:19], v[238:241], v[20:23]
	v_mfma_f32_16x16x32_bf16 v[20:23], v[24:27], v[234:237], v[170:173]
	v_mfma_f32_16x16x32_bf16 v[12:15], v[16:19], v[246:249], v[0:3]
	v_mfma_f32_16x16x32_bf16 v[0:3], v[24:27], v[242:245], v[4:7]
	v_mfma_f32_16x16x32_bf16 v[20:23], v[204:207], v[238:241], v[20:23]
	v_mfma_f32_16x16x32_bf16 v[4:7], v[204:207], v[246:249], v[0:3]
	v_mfma_f32_16x16x32_bf16 v[0:3], v[208:211], v[32:35], v[8:11]
	v_mfma_f32_16x16x32_bf16 v[56:59], v[212:215], v[40:43], v[0:3]
	v_mfma_f32_16x16x32_bf16 v[0:3], v[216:219], v[32:35], v[174:177]
	v_mfma_f32_16x16x32_bf16 v[48:51], v[220:223], v[40:43], v[0:3]
	v_mfma_f32_16x16x32_bf16 v[0:3], v[208:211], v[224:227], v[180:183]
	v_mfma_f32_16x16x32_bf16 v[40:43], v[212:215], v[228:231], v[0:3]
	v_mfma_f32_16x16x32_bf16 v[0:3], v[216:219], v[224:227], v[184:187]
	v_mfma_f32_16x16x32_bf16 v[32:35], v[220:223], v[228:231], v[0:3]
	v_mfma_f32_16x16x32_bf16 v[0:3], v[208:211], v[234:237], v[188:191]
	v_mfma_f32_16x16x32_bf16 v[24:27], v[212:215], v[238:241], v[0:3]
	v_mfma_f32_16x16x32_bf16 v[0:3], v[216:219], v[234:237], v[192:195]
	v_mfma_f32_16x16x32_bf16 v[16:19], v[220:223], v[238:241], v[0:3]
	v_mfma_f32_16x16x32_bf16 v[0:3], v[208:211], v[242:245], v[196:199]
	v_mfma_f32_16x16x32_bf16 v[8:11], v[212:215], v[246:249], v[0:3]
	v_mfma_f32_16x16x32_bf16 v[0:3], v[216:219], v[242:245], v[200:203]
	v_mfma_f32_16x16x32_bf16 v[0:3], v[220:223], v[246:249], v[0:3]
	s_barrier
	s_add_u32 s3, s0, 0x200
	s_addc_u32 s2, s1, 0
	s_add_u32 s0, s24, 0xc04000
	s_addc_u32 s1, s25, 0
	s_mov_b32 s18, 0
	.p2align	6

; template <class Epi, class Sched, bool ALIGN_EPI = false, bool SP2 = false>
; __device__ __forceinline__ void gemm_phase(PG8_LAS unsigned char* lds, const Gemm g, const Sched& S, const Epi& E) {
;     ...
;         const bool has_next = S.next(ui + 1, nxt);
;         const char* nA = has_next ? (const char*)g.A + (size_t)nxt.pm * tstepA : cA; const char* nB = has_next ? (const char*)g.Bt + (size_t)nxt.pn * tstepB : cB;
.LBB0_249:
	s_ashr_i32 s49, s48, 31
	s_lshl_b64 s[2:3], s[48:49], 15
	v_readlane_b32 s11, v255, 15
	s_add_u32 s50, s11, s2
	v_readlane_b32 s2, v255, 16
	s_addc_u32 s51, s2, s3
	s_ashr_i32 s47, s46, 31
	s_lshl_b64 s[2:3], s[46:47], 19
	s_add_u32 s52, s38, s2
	s_addc_u32 s53, s19, s3
	s_add_u32 s28, s42, 0x800000
	s_addc_u32 s29, s43, 0
	s_add_u32 s44, s42, 0xc00000
	s_addc_u32 s45, s43, 0
	s_add_i32 s99, 0, 0x10000
	s_and_b64 s[2:3], s[40:41], exec
	s_cselect_b32 s27, s51, s43
	s_cselect_b32 s47, s50, s42
	s_add_i32 vcc_hi, 0, 0x14000
	v_add_u32_e32 v130, s99, v97
	v_add_u32_e32 v131, vcc_hi, v97
	ds_read_b128 v[0:3], v130
	ds_read_b128 v[4:7], v130 offset:1024
	ds_read_b128 v[8:11], v130 offset:2048
	ds_read_b128 v[12:15], v130 offset:3072
	ds_read_b128 v[16:19], v131
	ds_read_b128 v[20:23], v131 offset:1024
	ds_read_b128 v[24:27], v131 offset:2048
	ds_read_b128 v[28:31], v131 offset:3072
	s_and_b64 s[2:3], s[40:41], exec
	s_cselect_b32 s49, s53, s25
	s_cselect_b32 s54, s52, s24
	s_add_u32 s2, s42, 0x404000
	s_addc_u32 s3, s43, 0
	s_add_i32 s55, s22, 0xc000
	s_mov_b32 m0, s55
	s_add_i32 s98, s22, 0xe000
	ds_read_b128 v[32:35], v151
	ds_read_b128 v[36:39], v151 offset:1024
	ds_read_b128 v[40:43], v151 offset:2048
	ds_read_b128 v[44:47], v151 offset:3072
	ds_read_b128 v[48:51], v151 offset:4096
	ds_read_b128 v[52:55], v151 offset:5120
	ds_read_b128 v[56:59], v151 offset:6144
	ds_read_b128 v[60:63], v151 offset:7168
	global_load_lds_dwordx4 v134, s[2:3]
	s_mov_b32 m0, s98
	s_nop 0
	global_load_lds_dwordx4 v138, s[2:3]
	s_waitcnt vmcnt(8)
	s_waitcnt lgkmcnt(0)
	s_barrier
	v_mfma_f32_16x16x32_bf16 v[84:87], v[8:11], v[48:51], 0
	v_mfma_f32_16x16x32_bf16 v[88:91], v[12:15], v[52:55], v[84:87]
	v_mfma_f32_16x16x32_bf16 v[84:87], v[0:3], v[56:59], 0
	v_mfma_f32_16x16x32_bf16 v[64:67], v[0:3], v[32:35], 0
	v_mfma_f32_16x16x32_bf16 v[68:71], v[8:11], v[32:35], 0
	v_mfma_f32_16x16x32_bf16 v[72:75], v[0:3], v[40:43], 0
	v_mfma_f32_16x16x32_bf16 v[76:79], v[8:11], v[40:43], 0
	v_mfma_f32_16x16x32_bf16 v[80:83], v[0:3], v[48:51], 0
	v_mfma_f32_16x16x32_bf16 v[92:95], v[4:7], v[60:63], v[84:87]
	v_mfma_f32_16x16x32_bf16 v[84:87], v[8:11], v[56:59], 0
	v_mfma_f32_16x16x32_bf16 v[64:67], v[4:7], v[36:39], v[64:67]
	v_mfma_f32_16x16x32_bf16 v[68:71], v[12:15], v[36:39], v[68:71]
	v_mfma_f32_16x16x32_bf16 v[72:75], v[4:7], v[44:47], v[72:75]
	v_mfma_f32_16x16x32_bf16 v[76:79], v[12:15], v[44:47], v[76:79]
	v_mfma_f32_16x16x32_bf16 v[80:83], v[4:7], v[52:55], v[80:83]
	v_mfma_f32_16x16x32_bf16 v[106:109], v[12:15], v[60:63], v[84:87]
	v_mfma_f32_16x16x32_bf16 v[84:87], v[16:19], v[32:35], 0
	v_mfma_f32_16x16x32_bf16 v[32:35], v[24:27], v[32:35], 0
	v_mfma_f32_16x16x32_bf16 v[110:113], v[20:23], v[36:39], v[84:87]
	v_mfma_f32_16x16x32_bf16 v[32:35], v[28:31], v[36:39], v[32:35]
	v_mfma_f32_16x16x32_bf16 v[36:39], v[16:19], v[40:43], 0
	v_mfma_f32_16x16x32_bf16 v[40:43], v[24:27], v[40:43], 0
	v_mfma_f32_16x16x32_bf16 v[36:39], v[20:23], v[44:47], v[36:39]
	v_mfma_f32_16x16x32_bf16 v[40:43], v[28:31], v[44:47], v[40:43]
	v_mfma_f32_16x16x32_bf16 v[44:47], v[16:19], v[48:51], 0
	v_mfma_f32_16x16x32_bf16 v[48:51], v[24:27], v[48:51], 0
	v_mfma_f32_16x16x32_bf16 v[44:47], v[20:23], v[52:55], v[44:47]
	v_mfma_f32_16x16x32_bf16 v[48:51], v[28:31], v[52:55], v[48:51]
	v_mfma_f32_16x16x32_bf16 v[52:55], v[16:19], v[56:59], 0
	v_mfma_f32_16x16x32_bf16 v[56:59], v[24:27], v[56:59], 0
	v_mfma_f32_16x16x32_bf16 v[52:55], v[20:23], v[60:63], v[52:55]
	v_mfma_f32_16x16x32_bf16 v[56:59], v[28:31], v[60:63], v[56:59]
	s_barrier
	v_lshl_add_u64 v[176:177], s[24:25], 0, v[136:137]
	s_mov_b64 s[2:3], 0x100
	s_add_i32 s99, s99, s10
	v_lshl_add_u64 v[132:133], v[176:177], 0, s[2:3]
	s_mov_b32 m0, s99
	v_lshl_add_u64 v[178:179], s[24:25], 0, v[140:141]
	s_add_i32 vcc_lo, s99, 0x2000
	ds_read_b128 v[60:63], v151 offset:16384
	ds_read_b128 v[84:87], v151 offset:17408
	ds_read_b128 v[98:101], v151 offset:18432
	ds_read_b128 v[102:105], v151 offset:19456
	ds_read_b128 v[114:117], v151 offset:20480
	ds_read_b128 v[118:121], v151 offset:21504
	ds_read_b128 v[122:125], v151 offset:22528
	ds_read_b128 v[126:129], v151 offset:23552
	global_load_lds_dwordx4 v[132:133], off
	v_lshl_add_u64 v[132:133], v[178:179], 0, s[2:3]
	s_add_u32 s2, s24, 0x40100
	s_mov_b32 m0, vcc_lo
	s_addc_u32 s3, s25, 0
	s_add_i32 vcc_hi, vcc_hi, s10
	global_load_lds_dwordx4 v[132:133], off
	s_mov_b32 m0, vcc_hi
	s_add_i32 s30, vcc_hi, 0x2000
	global_load_lds_dwordx4 v136, s[2:3]
	s_mov_b32 m0, s30
	s_mov_b64 s[34:35], 0x100
	global_load_lds_dwordx4 v140, s[2:3]
	s_mov_b32 m0, s22
	s_nop 0
	global_load_lds_dwordx4 v134, s[28:29]
	s_mov_b32 m0, s23
	s_nop 0
	global_load_lds_dwordx4 v138, s[28:29]
	s_waitcnt vmcnt(8)
	s_waitcnt lgkmcnt(0)
	s_barrier
	v_mfma_f32_16x16x32_bf16 v[146:149], v[0:3], v[60:63], 0
	v_mfma_f32_16x16x32_bf16 v[156:159], v[0:3], v[98:101], 0
	v_mfma_f32_16x16x32_bf16 v[164:167], v[0:3], v[114:117], 0
	v_mfma_f32_16x16x32_bf16 v[0:3], v[0:3], v[122:125], 0
	v_mfma_f32_16x16x32_bf16 v[146:149], v[4:7], v[84:87], v[146:149]
	v_mfma_f32_16x16x32_bf16 v[156:159], v[4:7], v[102:105], v[156:159]
	v_mfma_f32_16x16x32_bf16 v[164:167], v[4:7], v[118:121], v[164:167]
	v_mfma_f32_16x16x32_bf16 v[0:3], v[4:7], v[126:129], v[0:3]
	v_mfma_f32_16x16x32_bf16 v[4:7], v[8:11], v[122:125], 0
	v_mfma_f32_16x16x32_bf16 v[152:155], v[8:11], v[60:63], 0
	v_mfma_f32_16x16x32_bf16 v[160:163], v[8:11], v[98:101], 0
	v_mfma_f32_16x16x32_bf16 v[168:171], v[8:11], v[114:117], 0
	v_mfma_f32_16x16x32_bf16 v[8:11], v[12:15], v[126:129], v[4:7]
	v_mfma_f32_16x16x32_bf16 v[152:155], v[12:15], v[84:87], v[152:155]
	v_mfma_f32_16x16x32_bf16 v[160:163], v[12:15], v[102:105], v[160:163]
	v_mfma_f32_16x16x32_bf16 v[168:171], v[12:15], v[118:121], v[168:171]
	v_mfma_f32_16x16x32_bf16 v[4:7], v[16:19], v[60:63], 0
	v_mfma_f32_16x16x32_bf16 v[12:15], v[20:23], v[84:87], v[4:7]
	v_mfma_f32_16x16x32_bf16 v[4:7], v[24:27], v[60:63], 0
	v_mfma_f32_16x16x32_bf16 v[172:175], v[28:31], v[84:87], v[4:7]
	v_mfma_f32_16x16x32_bf16 v[4:7], v[16:19], v[98:101], 0
	v_mfma_f32_16x16x32_bf16 v[180:183], v[20:23], v[102:105], v[4:7]
	v_mfma_f32_16x16x32_bf16 v[4:7], v[24:27], v[98:101], 0
	v_mfma_f32_16x16x32_bf16 v[184:187], v[28:31], v[102:105], v[4:7]
	v_mfma_f32_16x16x32_bf16 v[4:7], v[16:19], v[114:117], 0
	v_mfma_f32_16x16x32_bf16 v[188:191], v[20:23], v[118:121], v[4:7]
	v_mfma_f32_16x16x32_bf16 v[4:7], v[24:27], v[114:117], 0
	v_mfma_f32_16x16x32_bf16 v[192:195], v[28:31], v[118:121], v[4:7]
	v_mfma_f32_16x16x32_bf16 v[4:7], v[16:19], v[122:125], 0
	v_mfma_f32_16x16x32_bf16 v[196:199], v[20:23], v[126:129], v[4:7]
	v_mfma_f32_16x16x32_bf16 v[4:7], v[24:27], v[122:125], 0
	v_mfma_f32_16x16x32_bf16 v[200:203], v[28:31], v[126:129], v[4:7]
	s_barrier
	s_add_i32 s31, 0, 0x18000
	s_add_i32 s13, 0, 0x1c000
	v_add_u32_e32 v132, s31, v97
	v_add_u32_e32 v133, s13, v97
	s_nop 0
	ds_read_b128 v[4:7], v132
	ds_read_b128 v[24:27], v132 offset:1024
	ds_read_b128 v[28:31], v132 offset:2048
	ds_read_b128 v[60:63], v132 offset:3072
	ds_read_b128 v[204:207], v133
	ds_read_b128 v[208:211], v133 offset:1024
	ds_read_b128 v[212:215], v133 offset:2048
	ds_read_b128 v[216:219], v133 offset:3072
	s_add_u32 s2, s42, 0x804000
	s_addc_u32 s3, s43, 0
	s_mov_b32 m0, s39
	ds_read_b128 v[16:19], v151 offset:32768
	ds_read_b128 v[20:23], v151 offset:33792
	ds_read_b128 v[220:223], v151 offset:34816
	ds_read_b128 v[224:227], v151 offset:35840
	ds_read_b128 v[228:231], v151 offset:36864
	ds_read_b128 v[234:237], v151 offset:37888
	ds_read_b128 v[238:241], v151 offset:38912
	ds_read_b128 v[242:245], v151 offset:39936
	global_load_lds_dwordx4 v134, s[2:3]
	s_mov_b32 m0, s56
	s_nop 0
	global_load_lds_dwordx4 v138, s[2:3]
	s_waitcnt vmcnt(8)
	s_waitcnt lgkmcnt(0)
	s_barrier
	v_mfma_f32_16x16x32_bf16 v[64:67], v[4:7], v[16:19], v[64:67]
	v_mfma_f32_16x16x32_bf16 v[118:121], v[24:27], v[20:23], v[64:67]
	v_mfma_f32_16x16x32_bf16 v[64:67], v[28:31], v[16:19], v[68:71]
	v_mfma_f32_16x16x32_bf16 v[114:117], v[60:63], v[20:23], v[64:67]
	v_mfma_f32_16x16x32_bf16 v[64:67], v[4:7], v[220:223], v[72:75]
	v_mfma_f32_16x16x32_bf16 v[102:105], v[24:27], v[224:227], v[64:67]
	v_mfma_f32_16x16x32_bf16 v[64:67], v[28:31], v[220:223], v[76:79]
	v_mfma_f32_16x16x32_bf16 v[98:101], v[60:63], v[224:227], v[64:67]
	v_mfma_f32_16x16x32_bf16 v[64:67], v[4:7], v[228:231], v[80:83]
	v_mfma_f32_16x16x32_bf16 v[84:87], v[24:27], v[234:237], v[64:67]
	v_mfma_f32_16x16x32_bf16 v[64:67], v[28:31], v[228:231], v[88:91]
	v_mfma_f32_16x16x32_bf16 v[80:83], v[60:63], v[234:237], v[64:67]
	v_mfma_f32_16x16x32_bf16 v[64:67], v[4:7], v[238:241], v[92:95]
	v_mfma_f32_16x16x32_bf16 v[68:71], v[24:27], v[242:245], v[64:67]
	v_mfma_f32_16x16x32_bf16 v[64:67], v[28:31], v[238:241], v[106:109]
	v_mfma_f32_16x16x32_bf16 v[64:67], v[60:63], v[242:245], v[64:67]
	v_mfma_f32_16x16x32_bf16 v[72:75], v[204:207], v[16:19], v[110:113]
	v_mfma_f32_16x16x32_bf16 v[16:19], v[212:215], v[16:19], v[32:35]
	v_mfma_f32_16x16x32_bf16 v[122:125], v[216:219], v[20:23], v[16:19]
	v_mfma_f32_16x16x32_bf16 v[16:19], v[204:207], v[220:223], v[36:39]
	v_mfma_f32_16x16x32_bf16 v[110:113], v[208:211], v[224:227], v[16:19]
	v_mfma_f32_16x16x32_bf16 v[16:19], v[212:215], v[220:223], v[40:43]
	v_mfma_f32_16x16x32_bf16 v[106:109], v[216:219], v[224:227], v[16:19]
	v_mfma_f32_16x16x32_bf16 v[16:19], v[204:207], v[228:231], v[44:47]
	v_mfma_f32_16x16x32_bf16 v[92:95], v[208:211], v[234:237], v[16:19]
	v_mfma_f32_16x16x32_bf16 v[16:19], v[212:215], v[228:231], v[48:51]
	v_mfma_f32_16x16x32_bf16 v[88:91], v[216:219], v[234:237], v[16:19]
	v_mfma_f32_16x16x32_bf16 v[16:19], v[204:207], v[238:241], v[52:55]
	v_mfma_f32_16x16x32_bf16 v[76:79], v[208:211], v[242:245], v[16:19]
	v_mfma_f32_16x16x32_bf16 v[16:19], v[212:215], v[238:241], v[56:59]
	v_mfma_f32_16x16x32_bf16 v[126:129], v[208:211], v[20:23], v[72:75]
	v_mfma_f32_16x16x32_bf16 v[72:75], v[216:219], v[242:245], v[16:19]
	s_barrier
; template <class Epi, class Sched, bool ALIGN_EPI = false, bool SP2 = false>
; __device__ __forceinline__ void gemm_phase(PG8_LAS unsigned char* lds, const Gemm g, const Sched& S, const Epi& E) {
;     ...
;         if constexpr (Epi::PEEL) {
;             const char* a1 = cA + kstepA; const char* a2 = cA + 2 * kstepA; const char* b2 = cB + 2 * kstepB; const char* a3 = a2 + kstepA; const char* b3 = b2 + kstepB;
;             PG8_ITER(8);
;         }
;         for (int t = (Epi::PEEL ? 2 : 0); t < nt; t += 2) {
;             const bool last = (t == nt - 2);
;             const char* a1 = cA + (size_t)(t + 1) * kstepA;
;             const char* a2 = last ? nA : cA + (size_t)(t + 2) * kstepA; const char* b2 = last ? nB : cB + (size_t)(t + 2) * kstepB;
;             const char* a3 = a2 + kstepA; const char* b3 = b2 + kstepB;
;             PG8_ITER(8);
	s_mov_b64 s[2:3], 0x180
	s_add_i32 s31, s31, s10
	s_nop 1
	v_lshl_add_u64 v[16:17], v[176:177], 0, s[2:3]
	s_mov_b32 m0, s31
	s_add_i32 s12, s31, 0x2000
	ds_read_b128 v[40:43], v151 offset:49152
	ds_read_b128 v[44:47], v151 offset:50176
	ds_read_b128 v[220:223], v151 offset:51200
	ds_read_b128 v[224:227], v151 offset:52224
	ds_read_b128 v[228:231], v151 offset:53248
	ds_read_b128 v[234:237], v151 offset:54272
	ds_read_b128 v[238:241], v151 offset:55296
	ds_read_b128 v[242:245], v151 offset:56320
	global_load_lds_dwordx4 v[16:17], off
	v_lshl_add_u64 v[16:17], v[178:179], 0, s[2:3]
	s_add_u32 s2, s24, 0x40180
	s_mov_b32 m0, s12
	s_addc_u32 s3, s25, 0
	s_add_i32 s13, s13, s10
	global_load_lds_dwordx4 v[16:17], off
	s_mov_b32 m0, s13
	s_add_i32 s11, s13, 0x2000
	global_load_lds_dwordx4 v136, s[2:3]
	s_mov_b32 m0, s11
	s_nop 0
	global_load_lds_dwordx4 v140, s[2:3]
	s_mov_b32 m0, s59
	s_nop 0
	global_load_lds_dwordx4 v134, s[44:45]
	s_mov_b32 m0, s96
	s_nop 0
	global_load_lds_dwordx4 v138, s[44:45]
	s_waitcnt vmcnt(8)
	s_waitcnt lgkmcnt(0)
	s_barrier
	v_mfma_f32_16x16x32_bf16 v[16:19], v[4:7], v[40:43], v[146:149]
	v_mfma_f32_16x16x32_bf16 v[52:55], v[24:27], v[44:47], v[16:19]
	v_mfma_f32_16x16x32_bf16 v[16:19], v[28:31], v[40:43], v[152:155]
	v_mfma_f32_16x16x32_bf16 v[48:51], v[60:63], v[44:47], v[16:19]
	v_mfma_f32_16x16x32_bf16 v[16:19], v[4:7], v[220:223], v[156:159]
	v_mfma_f32_16x16x32_bf16 v[36:39], v[24:27], v[224:227], v[16:19]
	v_mfma_f32_16x16x32_bf16 v[16:19], v[28:31], v[220:223], v[160:163]
	v_mfma_f32_16x16x32_bf16 v[32:35], v[60:63], v[224:227], v[16:19]
	v_mfma_f32_16x16x32_bf16 v[16:19], v[4:7], v[228:231], v[164:167]
	v_mfma_f32_16x16x32_bf16 v[0:3], v[4:7], v[238:241], v[0:3]
	v_mfma_f32_16x16x32_bf16 v[20:23], v[24:27], v[234:237], v[16:19]
	v_mfma_f32_16x16x32_bf16 v[16:19], v[28:31], v[228:231], v[168:171]
	v_mfma_f32_16x16x32_bf16 v[4:7], v[24:27], v[242:245], v[0:3]
	v_mfma_f32_16x16x32_bf16 v[0:3], v[28:31], v[238:241], v[8:11]
	v_mfma_f32_16x16x32_bf16 v[16:19], v[60:63], v[234:237], v[16:19]
	v_mfma_f32_16x16x32_bf16 v[0:3], v[60:63], v[242:245], v[0:3]
	v_mfma_f32_16x16x32_bf16 v[8:11], v[204:207], v[40:43], v[12:15]
	v_mfma_f32_16x16x32_bf16 v[60:63], v[208:211], v[44:47], v[8:11]
	v_mfma_f32_16x16x32_bf16 v[8:11], v[212:215], v[40:43], v[172:175]
	v_mfma_f32_16x16x32_bf16 v[56:59], v[216:219], v[44:47], v[8:11]
	v_mfma_f32_16x16x32_bf16 v[8:11], v[204:207], v[220:223], v[180:183]
	v_mfma_f32_16x16x32_bf16 v[44:47], v[208:211], v[224:227], v[8:11]
	v_mfma_f32_16x16x32_bf16 v[8:11], v[212:215], v[220:223], v[184:187]
	v_mfma_f32_16x16x32_bf16 v[40:43], v[216:219], v[224:227], v[8:11]
	v_mfma_f32_16x16x32_bf16 v[8:11], v[204:207], v[228:231], v[188:191]
	v_mfma_f32_16x16x32_bf16 v[28:31], v[208:211], v[234:237], v[8:11]
	v_mfma_f32_16x16x32_bf16 v[8:11], v[212:215], v[228:231], v[192:195]
	v_mfma_f32_16x16x32_bf16 v[24:27], v[216:219], v[234:237], v[8:11]
	v_mfma_f32_16x16x32_bf16 v[8:11], v[204:207], v[238:241], v[196:199]
	v_mfma_f32_16x16x32_bf16 v[12:15], v[208:211], v[242:245], v[8:11]
	v_mfma_f32_16x16x32_bf16 v[8:11], v[212:215], v[238:241], v[200:203]
	v_mfma_f32_16x16x32_bf16 v[8:11], v[216:219], v[242:245], v[8:11]
	s_barrier
	s_add_u32 s3, s24, 0x200
	s_addc_u32 s2, s25, 0
	s_add_u32 s24, s42, 0xc04000
	s_addc_u32 s25, s43, 0
	s_mov_b32 s18, 0
	.p2align	6

; template <class Epi, class Sched, bool ALIGN_EPI = false, bool SP2 = false>
; __device__ __forceinline__ void gemm_phase(PG8_LAS unsigned char* lds, const Gemm g, const Sched& S, const Epi& E) {
;     ...
; #pragma unroll
;         for (int a = 0; a < 2; ++a)
; #pragma unroll
;             for (int b = 0; b < 2; ++b)
; #pragma unroll
;                 for (int m = 0; m < 4; ++m)
; #pragma unroll
;                     for (int n = 0; n < 2; ++n) acc[a][b][m][n] = (f32x4){0.f, 0.f, 0.f, 0.f};
;         cur = nxt; cA = nA; cB = nB; ++ui;
.LBB0_344:
	s_add_u32 s58, s42, 0x100
	v_mov_b32_e32 v0, 0
	s_addc_u32 s59, s43, 0
	s_mov_b32 s10, 0
	v_mov_b32_e32 v1, v0
	v_mov_b32_e32 v2, v0
	v_mov_b32_e32 v3, v0
	v_mov_b32_e32 v4, v0
	v_mov_b32_e32 v5, v0
	v_mov_b32_e32 v6, v0
	v_mov_b32_e32 v7, v0
	v_mov_b32_e32 v16, v0
	v_mov_b32_e32 v17, v0
	v_mov_b32_e32 v18, v0
	v_mov_b32_e32 v19, v0
	v_mov_b32_e32 v20, v0
	v_mov_b32_e32 v21, v0
	s_waitcnt lgkmcnt(0)
	v_mov_b32_e32 v22, v0
	v_mov_b32_e32 v23, v0
	v_mov_b32_e32 v32, v0
	v_mov_b32_e32 v33, v0
	v_mov_b32_e32 v34, v0
	v_mov_b32_e32 v35, v0
	v_mov_b32_e32 v36, v0
	v_mov_b32_e32 v37, v0
	v_mov_b32_e32 v38, v0
	v_mov_b32_e32 v39, v0
	v_mov_b32_e32 v48, v0
	v_mov_b32_e32 v49, v0
	v_mov_b32_e32 v50, v0
	v_mov_b32_e32 v51, v0
	v_mov_b32_e32 v52, v0
	v_mov_b32_e32 v53, v0
	v_mov_b32_e32 v54, v0
	v_mov_b32_e32 v55, v0
	v_mov_b32_e32 v8, v0
	v_mov_b32_e32 v9, v0
	v_mov_b32_e32 v10, v0
	v_mov_b32_e32 v11, v0
	v_mov_b32_e32 v12, v0
	v_mov_b32_e32 v13, v0
	v_mov_b32_e32 v14, v0
	v_mov_b32_e32 v15, v0
	v_mov_b32_e32 v24, v0
	v_mov_b32_e32 v25, v0
	v_mov_b32_e32 v26, v0
	v_mov_b32_e32 v27, v0
	v_mov_b32_e32 v28, v0
	v_mov_b32_e32 v29, v0
	v_mov_b32_e32 v30, v0
	v_mov_b32_e32 v31, v0
	v_mov_b32_e32 v40, v0
	v_mov_b32_e32 v41, v0
	v_mov_b32_e32 v42, v0
	v_mov_b32_e32 v43, v0
	v_mov_b32_e32 v44, v0
	v_mov_b32_e32 v45, v0
	v_mov_b32_e32 v46, v0
	v_mov_b32_e32 v47, v0
	v_mov_b32_e32 v56, v0
	v_mov_b32_e32 v57, v0
	v_mov_b32_e32 v58, v0
	v_mov_b32_e32 v59, v0
	v_mov_b32_e32 v60, v0
	v_mov_b32_e32 v61, v0
	v_mov_b32_e32 v62, v0
	v_mov_b32_e32 v63, v0
	v_mov_b32_e32 v64, v0
	v_mov_b32_e32 v65, v0
	v_mov_b32_e32 v66, v0
	v_mov_b32_e32 v67, v0
	v_mov_b32_e32 v68, v0
	v_mov_b32_e32 v69, v0
	v_mov_b32_e32 v70, v0
	v_mov_b32_e32 v71, v0
	v_mov_b32_e32 v80, v0
	v_mov_b32_e32 v81, v0
	v_mov_b32_e32 v82, v0
	v_mov_b32_e32 v83, v0
	v_mov_b32_e32 v84, v0
	v_mov_b32_e32 v85, v0
	v_mov_b32_e32 v86, v0
	v_mov_b32_e32 v87, v0
	v_mov_b32_e32 v98, v0
	v_mov_b32_e32 v99, v0
	v_mov_b32_e32 v100, v0
	v_mov_b32_e32 v101, v0
	v_mov_b32_e32 v102, v0
	v_mov_b32_e32 v103, v0
	v_mov_b32_e32 v104, v0
	v_mov_b32_e32 v105, v0
	v_mov_b32_e32 v114, v0
	v_mov_b32_e32 v115, v0
	v_mov_b32_e32 v116, v0
	v_mov_b32_e32 v117, v0
	v_mov_b32_e32 v118, v0
	v_mov_b32_e32 v119, v0
	v_mov_b32_e32 v120, v0
	v_mov_b32_e32 v121, v0
	v_mov_b32_e32 v72, v0
	v_mov_b32_e32 v73, v0
	v_mov_b32_e32 v74, v0
	v_mov_b32_e32 v75, v0
	v_mov_b32_e32 v76, v0
	v_mov_b32_e32 v77, v0
	v_mov_b32_e32 v78, v0
	v_mov_b32_e32 v79, v0
	v_mov_b32_e32 v88, v0
	v_mov_b32_e32 v89, v0
	v_mov_b32_e32 v90, v0
	v_mov_b32_e32 v91, v0
	v_mov_b32_e32 v92, v0
	v_mov_b32_e32 v93, v0
	v_mov_b32_e32 v94, v0
	v_mov_b32_e32 v95, v0
	v_mov_b32_e32 v106, v0
	v_mov_b32_e32 v107, v0
	v_mov_b32_e32 v108, v0
	v_mov_b32_e32 v109, v0
	v_mov_b32_e32 v110, v0
	v_mov_b32_e32 v111, v0
	v_mov_b32_e32 v112, v0
	v_mov_b32_e32 v113, v0
	v_mov_b32_e32 v130, v0
	v_mov_b32_e32 v131, v0
	v_mov_b32_e32 v132, v0
	v_mov_b32_e32 v133, v0
	v_mov_b32_e32 v134, v0
	v_mov_b32_e32 v135, v0
	v_mov_b32_e32 v136, v0
	v_mov_b32_e32 v137, v0
	v_add_u32_e32 v218, 0x10000, v97
	v_add_u32_e32 v219, 0x14000, v97
	v_add_u32_e32 v220, 0x18000, v97
	v_add_u32_e32 v221, 0x1c000, v97
	s_branch .LBB0_346
	.p2align	6

; template <class Epi, class Sched, bool ALIGN_EPI = false, bool SP2 = false>
; __device__ __forceinline__ void gemm_phase(PG8_LAS unsigned char* lds, const Gemm g, const Sched& S, const Epi& E) {
;     ...
;         const bool has_next = S.next(ui + 1, nxt);
;         const char* nA = has_next ? (const char*)g.A + (size_t)nxt.pm * tstepA : cA; const char* nB = has_next ? (const char*)g.Bt + (size_t)nxt.pn * tstepB : cB;
.LBB0_477:
	s_ashr_i32 s27, s26, 31
	s_lshl_b64 s[2:3], s[26:27], 15
	v_readlane_b32 s10, v255, 15
	s_add_u32 s28, s10, s2
	v_readlane_b32 s2, v255, 16
	s_addc_u32 s29, s2, s3
	s_ashr_i32 s25, s24, 31
	s_lshl_b64 s[2:3], s[24:25], 19
	s_add_u32 s30, s19, s2
	s_addc_u32 s31, s22, s3
	s_add_u32 s44, s34, 0x800000
	s_addc_u32 s45, s35, 0
	s_add_u32 s42, s34, 0xc00000
	s_addc_u32 s43, s35, 0
	s_add_i32 s61, 0, 0x10000
	s_and_b64 s[2:3], s[40:41], exec
	s_cselect_b32 s25, s29, s35
	s_cselect_b32 s27, s28, s34
	s_add_i32 s97, 0, 0x14000
	v_add_u32_e32 v142, s61, v97
	v_add_u32_e32 v143, s97, v97
	ds_read_b128 v[0:3], v142
	ds_read_b128 v[4:7], v142 offset:1024
	ds_read_b128 v[8:11], v142 offset:2048
	ds_read_b128 v[12:15], v142 offset:3072
	ds_read_b128 v[16:19], v143
	ds_read_b128 v[20:23], v143 offset:1024
	ds_read_b128 v[24:27], v143 offset:2048
	ds_read_b128 v[28:31], v143 offset:3072
	s_and_b64 s[2:3], s[40:41], exec
	s_cselect_b32 s57, s31, s1
	s_cselect_b32 s58, s30, s0
	s_add_u32 s2, s34, 0x404000
	s_addc_u32 s3, s35, 0
	s_add_i32 s59, s23, 0xc000
	s_mov_b32 m0, s59
	s_add_i32 s60, s23, 0xe000
	ds_read_b128 v[32:35], v156
	ds_read_b128 v[36:39], v156 offset:1024
	ds_read_b128 v[40:43], v156 offset:2048
	ds_read_b128 v[44:47], v156 offset:3072
	ds_read_b128 v[48:51], v156 offset:4096
	ds_read_b128 v[52:55], v156 offset:5120
	ds_read_b128 v[56:59], v156 offset:6144
	ds_read_b128 v[60:63], v156 offset:7168
	global_load_lds_dwordx4 v130, s[2:3]
	s_mov_b32 m0, s60
	s_nop 0
	global_load_lds_dwordx4 v134, s[2:3]
	s_waitcnt vmcnt(8)
	s_waitcnt lgkmcnt(0)
	s_barrier
	v_mfma_f32_16x16x32_bf16 v[88:91], v[0:3], v[56:59], 0
	v_mfma_f32_16x16x32_bf16 v[64:67], v[0:3], v[32:35], 0
	v_mfma_f32_16x16x32_bf16 v[68:71], v[8:11], v[32:35], 0
	v_mfma_f32_16x16x32_bf16 v[72:75], v[0:3], v[40:43], 0
	v_mfma_f32_16x16x32_bf16 v[76:79], v[8:11], v[40:43], 0
	v_mfma_f32_16x16x32_bf16 v[80:83], v[0:3], v[48:51], 0
	v_mfma_f32_16x16x32_bf16 v[84:87], v[8:11], v[48:51], 0
	v_mfma_f32_16x16x32_bf16 v[92:95], v[4:7], v[60:63], v[88:91]
	v_mfma_f32_16x16x32_bf16 v[88:91], v[8:11], v[56:59], 0
	v_mfma_f32_16x16x32_bf16 v[64:67], v[4:7], v[36:39], v[64:67]
	v_mfma_f32_16x16x32_bf16 v[68:71], v[12:15], v[36:39], v[68:71]
	v_mfma_f32_16x16x32_bf16 v[72:75], v[4:7], v[44:47], v[72:75]
	v_mfma_f32_16x16x32_bf16 v[76:79], v[12:15], v[44:47], v[76:79]
	v_mfma_f32_16x16x32_bf16 v[80:83], v[4:7], v[52:55], v[80:83]
	v_mfma_f32_16x16x32_bf16 v[84:87], v[12:15], v[52:55], v[84:87]
	v_mfma_f32_16x16x32_bf16 v[102:105], v[12:15], v[60:63], v[88:91]
	v_mfma_f32_16x16x32_bf16 v[88:91], v[16:19], v[32:35], 0
	v_mfma_f32_16x16x32_bf16 v[32:35], v[24:27], v[32:35], 0
	v_mfma_f32_16x16x32_bf16 v[110:113], v[20:23], v[36:39], v[88:91]
	v_mfma_f32_16x16x32_bf16 v[32:35], v[28:31], v[36:39], v[32:35]
	v_mfma_f32_16x16x32_bf16 v[36:39], v[16:19], v[40:43], 0
	v_mfma_f32_16x16x32_bf16 v[40:43], v[24:27], v[40:43], 0
	v_mfma_f32_16x16x32_bf16 v[36:39], v[20:23], v[44:47], v[36:39]
	v_mfma_f32_16x16x32_bf16 v[40:43], v[28:31], v[44:47], v[40:43]
	v_mfma_f32_16x16x32_bf16 v[44:47], v[16:19], v[48:51], 0
	v_mfma_f32_16x16x32_bf16 v[48:51], v[24:27], v[48:51], 0
	v_mfma_f32_16x16x32_bf16 v[44:47], v[20:23], v[52:55], v[44:47]
	v_mfma_f32_16x16x32_bf16 v[48:51], v[28:31], v[52:55], v[48:51]
	v_mfma_f32_16x16x32_bf16 v[52:55], v[16:19], v[56:59], 0
	v_mfma_f32_16x16x32_bf16 v[56:59], v[24:27], v[56:59], 0
	v_mfma_f32_16x16x32_bf16 v[52:55], v[20:23], v[60:63], v[52:55]
	v_mfma_f32_16x16x32_bf16 v[56:59], v[28:31], v[60:63], v[56:59]
	s_barrier
	v_lshl_add_u64 v[154:155], s[0:1], 0, v[132:133]
	s_mov_b64 s[2:3], 0x100
	s_add_i32 s61, s61, s9
	v_lshl_add_u64 v[144:145], v[154:155], 0, s[2:3]
	s_mov_b32 m0, s61
	v_lshl_add_u64 v[178:179], s[0:1], 0, v[136:137]
	s_add_i32 s96, s61, 0x2000
	ds_read_b128 v[60:63], v156 offset:16384
	ds_read_b128 v[88:91], v156 offset:17408
	ds_read_b128 v[98:101], v156 offset:18432
	ds_read_b128 v[106:109], v156 offset:19456
	ds_read_b128 v[114:117], v156 offset:20480
	ds_read_b128 v[118:121], v156 offset:21504
	ds_read_b128 v[122:125], v156 offset:22528
	ds_read_b128 v[126:129], v156 offset:23552
	global_load_lds_dwordx4 v[144:145], off
	v_lshl_add_u64 v[144:145], v[178:179], 0, s[2:3]
	s_add_u32 s2, s0, 0x40100
	s_mov_b32 m0, s96
	s_addc_u32 s3, s1, 0
	s_add_i32 s97, s97, s9
	global_load_lds_dwordx4 v[144:145], off
	s_mov_b32 m0, s97
	s_add_i32 s98, s97, 0x2000
	global_load_lds_dwordx4 v132, s[2:3]
	s_mov_b32 m0, s98
	s_nop 0
	global_load_lds_dwordx4 v136, s[2:3]
	s_mov_b32 m0, s23
	s_nop 0
	global_load_lds_dwordx4 v130, s[44:45]
	s_mov_b32 m0, s39
	s_nop 0
	global_load_lds_dwordx4 v134, s[44:45]
	s_waitcnt vmcnt(8)
	s_waitcnt lgkmcnt(0)
	s_barrier
	v_mfma_f32_16x16x32_bf16 v[144:147], v[0:3], v[60:63], 0
	v_mfma_f32_16x16x32_bf16 v[158:161], v[0:3], v[98:101], 0
	v_mfma_f32_16x16x32_bf16 v[166:169], v[0:3], v[114:117], 0
	v_mfma_f32_16x16x32_bf16 v[0:3], v[0:3], v[122:125], 0
	v_mfma_f32_16x16x32_bf16 v[146:149], v[4:7], v[88:91], v[144:147]
	v_mfma_f32_16x16x32_bf16 v[158:161], v[4:7], v[106:109], v[158:161]
	v_mfma_f32_16x16x32_bf16 v[166:169], v[4:7], v[118:121], v[166:169]
	v_mfma_f32_16x16x32_bf16 v[0:3], v[4:7], v[126:129], v[0:3]
	v_mfma_f32_16x16x32_bf16 v[4:7], v[8:11], v[122:125], 0
	v_mfma_f32_16x16x32_bf16 v[150:153], v[8:11], v[60:63], 0
	v_mfma_f32_16x16x32_bf16 v[162:165], v[8:11], v[98:101], 0
	v_mfma_f32_16x16x32_bf16 v[170:173], v[8:11], v[114:117], 0
	v_mfma_f32_16x16x32_bf16 v[4:7], v[12:15], v[126:129], v[4:7]
	v_mfma_f32_16x16x32_bf16 v[150:153], v[12:15], v[88:91], v[150:153]
	v_mfma_f32_16x16x32_bf16 v[162:165], v[12:15], v[106:109], v[162:165]
	v_mfma_f32_16x16x32_bf16 v[170:173], v[12:15], v[118:121], v[170:173]
	v_mfma_f32_16x16x32_bf16 v[8:11], v[16:19], v[60:63], 0
	v_mfma_f32_16x16x32_bf16 v[12:15], v[20:23], v[88:91], v[8:11]
	v_mfma_f32_16x16x32_bf16 v[8:11], v[24:27], v[60:63], 0
	v_mfma_f32_16x16x32_bf16 v[174:177], v[28:31], v[88:91], v[8:11]
	v_mfma_f32_16x16x32_bf16 v[8:11], v[16:19], v[98:101], 0
	v_mfma_f32_16x16x32_bf16 v[188:191], v[20:23], v[106:109], v[8:11]
	v_mfma_f32_16x16x32_bf16 v[8:11], v[24:27], v[98:101], 0
	v_mfma_f32_16x16x32_bf16 v[192:195], v[28:31], v[106:109], v[8:11]
	v_mfma_f32_16x16x32_bf16 v[8:11], v[16:19], v[114:117], 0
	v_mfma_f32_16x16x32_bf16 v[196:199], v[20:23], v[118:121], v[8:11]
	v_mfma_f32_16x16x32_bf16 v[8:11], v[24:27], v[114:117], 0
	v_mfma_f32_16x16x32_bf16 v[200:203], v[28:31], v[118:121], v[8:11]
	v_mfma_f32_16x16x32_bf16 v[8:11], v[16:19], v[122:125], 0
	v_mfma_f32_16x16x32_bf16 v[204:207], v[20:23], v[126:129], v[8:11]
	v_mfma_f32_16x16x32_bf16 v[8:11], v[24:27], v[122:125], 0
	v_mfma_f32_16x16x32_bf16 v[208:211], v[28:31], v[126:129], v[8:11]
	s_barrier
	s_add_i32 s99, 0, 0x18000
	s_add_i32 vcc_hi, 0, 0x1c000
	v_add_u32_e32 v144, s99, v97
	v_add_u32_e32 v145, vcc_hi, v97
	s_nop 0
	ds_read_b128 v[8:11], v144
	ds_read_b128 v[20:23], v144 offset:1024
	ds_read_b128 v[28:31], v144 offset:2048
	ds_read_b128 v[212:215], v144 offset:3072
	ds_read_b128 v[216:219], v145
	ds_read_b128 v[220:223], v145 offset:1024
	ds_read_b128 v[234:237], v145 offset:2048
	ds_read_b128 v[238:241], v145 offset:3072
	s_add_u32 s2, s34, 0x804000
	s_addc_u32 s3, s35, 0
	s_mov_b32 m0, s46
	ds_read_b128 v[16:19], v156 offset:32768
	ds_read_b128 v[24:27], v156 offset:33792
	ds_read_b128 v[242:245], v156 offset:34816
	ds_read_b128 v[246:249], v156 offset:35840
	ds_read_b128 v[228:231], v156 offset:36864
	ds_read_b128 v[180:183], v156 offset:37888
	ds_read_b128 v[184:187], v156 offset:38912
	ds_read_b128 v[224:227], v156 offset:39936
	global_load_lds_dwordx4 v130, s[2:3]
	s_mov_b32 m0, s47
	s_nop 0
	global_load_lds_dwordx4 v134, s[2:3]
	s_waitcnt vmcnt(8)
	s_waitcnt lgkmcnt(0)
	s_barrier
	v_mfma_f32_16x16x32_bf16 v[60:63], v[8:11], v[16:19], v[64:67]
	v_mfma_f32_16x16x32_bf16 v[122:125], v[20:23], v[24:27], v[60:63]
	v_mfma_f32_16x16x32_bf16 v[60:63], v[28:31], v[16:19], v[68:71]
	v_mfma_f32_16x16x32_bf16 v[114:117], v[212:215], v[24:27], v[60:63]
	v_mfma_f32_16x16x32_bf16 v[60:63], v[8:11], v[242:245], v[72:75]
	v_mfma_f32_16x16x32_bf16 v[106:109], v[20:23], v[246:249], v[60:63]
	v_mfma_f32_16x16x32_bf16 v[60:63], v[28:31], v[242:245], v[76:79]
	v_mfma_f32_16x16x32_bf16 v[98:101], v[212:215], v[246:249], v[60:63]
	v_mfma_f32_16x16x32_bf16 v[60:63], v[8:11], v[228:231], v[80:83]
	v_mfma_f32_16x16x32_bf16 v[88:91], v[20:23], v[180:183], v[60:63]
	v_mfma_f32_16x16x32_bf16 v[60:63], v[28:31], v[228:231], v[84:87]
	v_mfma_f32_16x16x32_bf16 v[80:83], v[212:215], v[180:183], v[60:63]
	v_mfma_f32_16x16x32_bf16 v[60:63], v[8:11], v[184:187], v[92:95]
	v_mfma_f32_16x16x32_bf16 v[72:75], v[20:23], v[224:227], v[60:63]
	v_mfma_f32_16x16x32_bf16 v[60:63], v[28:31], v[184:187], v[102:105]
	v_mfma_f32_16x16x32_bf16 v[60:63], v[212:215], v[224:227], v[60:63]
	v_mfma_f32_16x16x32_bf16 v[64:67], v[216:219], v[16:19], v[110:113]
	v_mfma_f32_16x16x32_bf16 v[16:19], v[234:237], v[16:19], v[32:35]
	v_mfma_f32_16x16x32_bf16 v[118:121], v[238:241], v[24:27], v[16:19]
	v_mfma_f32_16x16x32_bf16 v[16:19], v[216:219], v[242:245], v[36:39]
	v_mfma_f32_16x16x32_bf16 v[110:113], v[220:223], v[246:249], v[16:19]
	v_mfma_f32_16x16x32_bf16 v[16:19], v[234:237], v[242:245], v[40:43]
	v_mfma_f32_16x16x32_bf16 v[102:105], v[238:241], v[246:249], v[16:19]
	v_mfma_f32_16x16x32_bf16 v[16:19], v[216:219], v[228:231], v[44:47]
	v_mfma_f32_16x16x32_bf16 v[92:95], v[220:223], v[180:183], v[16:19]
	v_mfma_f32_16x16x32_bf16 v[16:19], v[234:237], v[228:231], v[48:51]
	v_mfma_f32_16x16x32_bf16 v[84:87], v[238:241], v[180:183], v[16:19]
	v_mfma_f32_16x16x32_bf16 v[16:19], v[216:219], v[184:187], v[52:55]
	v_mfma_f32_16x16x32_bf16 v[76:79], v[220:223], v[224:227], v[16:19]
	v_mfma_f32_16x16x32_bf16 v[16:19], v[234:237], v[184:187], v[56:59]
	v_mfma_f32_16x16x32_bf16 v[126:129], v[220:223], v[24:27], v[64:67]
	v_mfma_f32_16x16x32_bf16 v[68:71], v[238:241], v[224:227], v[16:19]
	s_barrier
; template <class Epi, class Sched, bool ALIGN_EPI = false, bool SP2 = false>
; __device__ __forceinline__ void gemm_phase(PG8_LAS unsigned char* lds, const Gemm g, const Sched& S, const Epi& E) {
;     ...
;         if constexpr (Epi::PEEL) {
;             const char* a1 = cA + kstepA; const char* a2 = cA + 2 * kstepA; const char* b2 = cB + 2 * kstepB; const char* a3 = a2 + kstepA; const char* b3 = b2 + kstepB;
;             PG8_ITER(8);
;         }
;         for (int t = (Epi::PEEL ? 2 : 0); t < nt; t += 2) {
;             const bool last = (t == nt - 2);
;             const char* a1 = cA + (size_t)(t + 1) * kstepA;
;             const char* a2 = last ? nA : cA + (size_t)(t + 2) * kstepA; const char* b2 = last ? nB : cB + (size_t)(t + 2) * kstepB;
;             const char* a3 = a2 + kstepA; const char* b3 = b2 + kstepB;
;             PG8_ITER(8);
	s_mov_b64 s[2:3], 0x180
	s_add_i32 s99, s99, s9
	s_nop 1
	v_lshl_add_u64 v[16:17], v[154:155], 0, s[2:3]
	s_mov_b32 m0, s99
	s_add_i32 vcc_lo, s99, 0x2000
	ds_read_b128 v[36:39], v156 offset:49152
	ds_read_b128 v[44:47], v156 offset:50176
	ds_read_b128 v[180:183], v156 offset:51200
	ds_read_b128 v[184:187], v156 offset:52224
	ds_read_b128 v[224:227], v156 offset:53248
	ds_read_b128 v[228:231], v156 offset:54272
	ds_read_b128 v[242:245], v156 offset:55296
	ds_read_b128 v[246:249], v156 offset:56320
	global_load_lds_dwordx4 v[16:17], off
	v_lshl_add_u64 v[16:17], v[178:179], 0, s[2:3]
	s_add_u32 s2, s0, 0x40180
	s_mov_b32 m0, vcc_lo
	s_addc_u32 s3, s1, 0
	s_add_i32 vcc_hi, vcc_hi, s9
	global_load_lds_dwordx4 v[16:17], off
	s_mov_b32 m0, vcc_hi
	s_add_i32 s38, vcc_hi, 0x2000
	global_load_lds_dwordx4 v132, s[2:3]
	s_mov_b32 m0, s38
	s_nop 0
	global_load_lds_dwordx4 v136, s[2:3]
	s_mov_b32 m0, s49
	s_nop 0
	global_load_lds_dwordx4 v130, s[42:43]
	s_mov_b32 m0, s50
	s_nop 0
	global_load_lds_dwordx4 v134, s[42:43]
	s_waitcnt vmcnt(8)
	s_waitcnt lgkmcnt(0)
	s_barrier
	v_mfma_f32_16x16x32_bf16 v[16:19], v[8:11], v[36:39], v[146:149]
	v_mfma_f32_16x16x32_bf16 v[56:59], v[20:23], v[44:47], v[16:19]
	v_mfma_f32_16x16x32_bf16 v[16:19], v[28:31], v[36:39], v[150:153]
	v_mfma_f32_16x16x32_bf16 v[48:51], v[212:215], v[44:47], v[16:19]
	v_mfma_f32_16x16x32_bf16 v[16:19], v[8:11], v[180:183], v[158:161]
	v_mfma_f32_16x16x32_bf16 v[40:43], v[20:23], v[184:187], v[16:19]
	v_mfma_f32_16x16x32_bf16 v[16:19], v[28:31], v[180:183], v[162:165]
	v_mfma_f32_16x16x32_bf16 v[32:35], v[212:215], v[184:187], v[16:19]
	v_mfma_f32_16x16x32_bf16 v[16:19], v[8:11], v[224:227], v[166:169]
	v_mfma_f32_16x16x32_bf16 v[0:3], v[8:11], v[242:245], v[0:3]
	v_mfma_f32_16x16x32_bf16 v[24:27], v[20:23], v[228:231], v[16:19]
	v_mfma_f32_16x16x32_bf16 v[16:19], v[28:31], v[224:227], v[170:173]
	v_mfma_f32_16x16x32_bf16 v[8:11], v[20:23], v[246:249], v[0:3]
	v_mfma_f32_16x16x32_bf16 v[0:3], v[28:31], v[242:245], v[4:7]
	v_mfma_f32_16x16x32_bf16 v[16:19], v[212:215], v[228:231], v[16:19]
	v_mfma_f32_16x16x32_bf16 v[0:3], v[212:215], v[246:249], v[0:3]
	v_mfma_f32_16x16x32_bf16 v[4:7], v[216:219], v[36:39], v[12:15]
	v_mfma_f32_16x16x32_bf16 v[64:67], v[220:223], v[44:47], v[4:7]
	v_mfma_f32_16x16x32_bf16 v[4:7], v[234:237], v[36:39], v[174:177]
	v_mfma_f32_16x16x32_bf16 v[52:55], v[238:241], v[44:47], v[4:7]
	v_mfma_f32_16x16x32_bf16 v[4:7], v[216:219], v[180:183], v[188:191]
	v_mfma_f32_16x16x32_bf16 v[44:47], v[220:223], v[184:187], v[4:7]
	v_mfma_f32_16x16x32_bf16 v[4:7], v[234:237], v[180:183], v[192:195]
	v_mfma_f32_16x16x32_bf16 v[36:39], v[238:241], v[184:187], v[4:7]
	v_mfma_f32_16x16x32_bf16 v[4:7], v[216:219], v[224:227], v[196:199]
	v_mfma_f32_16x16x32_bf16 v[28:31], v[220:223], v[228:231], v[4:7]
	v_mfma_f32_16x16x32_bf16 v[4:7], v[234:237], v[224:227], v[200:203]
	v_mfma_f32_16x16x32_bf16 v[20:23], v[238:241], v[228:231], v[4:7]
	v_mfma_f32_16x16x32_bf16 v[4:7], v[216:219], v[242:245], v[204:207]
	v_mfma_f32_16x16x32_bf16 v[12:15], v[220:223], v[246:249], v[4:7]
	v_mfma_f32_16x16x32_bf16 v[4:7], v[234:237], v[242:245], v[208:211]
	v_mfma_f32_16x16x32_bf16 v[4:7], v[238:241], v[246:249], v[4:7]
	s_barrier
	s_add_u32 s3, s0, 0x200
	s_addc_u32 s2, s1, 0
	s_add_u32 s0, s34, 0xc04000
	s_addc_u32 s1, s35, 0
	s_mov_b32 s18, 0
	.p2align	6
